# P3: epilogue stores drain under next unit K-tile 0 (first-iteration vmcnt relaxed, unit-loop vmcnt(0) hoisted)
# speedup vs baseline: 1.0067x; 1.0025x over previous
.LBB0_1083:
	s_add_u32 s24, s22, 0xfffc0080
	s_addc_u32 s25, s23, -1
	s_add_i32 s54, 0, 0x10000
	s_cmp_eq_u32 s53, 12
	s_cselect_b32 s27, s15, s25
	s_cselect_b32 s26, s49, s24
	v_add_u32_e32 v140, s54, v141
	s_cselect_b32 s25, s13, s52
	s_cselect_b32 s24, s50, s51
	s_add_i32 s56, 0, 0x14000
	ds_read_b128 v[144:147], v140
	ds_read_b128 v[148:151], v140 offset:1024
	ds_read_b128 v[152:155], v140 offset:2048
	ds_read_b128 v[156:159], v140 offset:3072
	v_add_u32_e32 v140, s56, v141
	ds_read_b128 v[160:163], v140
	ds_read_b128 v[164:167], v140 offset:1024
	ds_read_b128 v[168:171], v140 offset:2048
	ds_read_b128 v[172:175], v140 offset:3072
	v_lshl_add_u64 v[196:197], s[22:23], 0, v[136:137]
	s_add_i32 m0, s38, 0xc000
	ds_read_b128 v[176:179], v143
	ds_read_b128 v[180:183], v143 offset:1024
	ds_read_b128 v[184:187], v143 offset:2048
	ds_read_b128 v[188:191], v143 offset:3072
	ds_read_b128 v[192:195], v143 offset:4096
	ds_read_b128 v[202:205], v143 offset:5120
	ds_read_b128 v[214:217], v143 offset:6144
	ds_read_b128 v[224:227], v143 offset:7168
	global_load_lds_dwordx4 v[196:197], off
	v_lshl_add_u64 v[196:197], s[22:23], 0, v[138:139]
	s_add_i32 m0, s38, 0xe000
	s_nop 0
	global_load_lds_dwordx4 v[196:197], off
	s_cmp_eq_u32 s53, -2
	s_cbranch_scc1 .Lp3w_f0
	s_waitcnt vmcnt(8)
	s_branch .Lp3w_j0
.Lp3w_f0:
	s_waitcnt vmcnt(19)
.Lp3w_j0:
	s_waitcnt lgkmcnt(0)
	s_barrier
	s_setprio 1
	s_waitcnt lgkmcnt(0)
	v_mfma_f32_16x16x32_bf16 v[126:129], v[144:147], v[176:179], v[126:129]
	v_mfma_f32_16x16x32_bf16 v[118:121], v[152:155], v[176:179], v[118:121]
	v_mfma_f32_16x16x32_bf16 v[110:113], v[144:147], v[184:187], v[110:113]
	v_mfma_f32_16x16x32_bf16 v[102:105], v[152:155], v[184:187], v[102:105]
	v_mfma_f32_16x16x32_bf16 v[94:97], v[144:147], v[192:195], v[94:97]
	v_mfma_f32_16x16x32_bf16 v[86:89], v[152:155], v[192:195], v[86:89]
	v_mfma_f32_16x16x32_bf16 v[78:81], v[144:147], v[214:217], v[78:81]
	v_mfma_f32_16x16x32_bf16 v[70:73], v[152:155], v[214:217], v[70:73]
	v_mfma_f32_16x16x32_bf16 v[126:129], v[148:151], v[180:183], v[126:129]
	v_mfma_f32_16x16x32_bf16 v[118:121], v[156:159], v[180:183], v[118:121]
	v_mfma_f32_16x16x32_bf16 v[110:113], v[148:151], v[188:191], v[110:113]
	v_mfma_f32_16x16x32_bf16 v[102:105], v[156:159], v[188:191], v[102:105]
	v_mfma_f32_16x16x32_bf16 v[94:97], v[148:151], v[202:205], v[94:97]
	v_mfma_f32_16x16x32_bf16 v[86:89], v[156:159], v[202:205], v[86:89]
	v_mfma_f32_16x16x32_bf16 v[78:81], v[148:151], v[224:227], v[78:81]
	v_mfma_f32_16x16x32_bf16 v[70:73], v[156:159], v[224:227], v[70:73]
	s_setprio 0
	s_setprio 1
	v_mfma_f32_16x16x32_bf16 v[122:125], v[160:163], v[176:179], v[122:125]
	v_mfma_f32_16x16x32_bf16 v[114:117], v[168:171], v[176:179], v[114:117]
	v_mfma_f32_16x16x32_bf16 v[106:109], v[160:163], v[184:187], v[106:109]
	v_mfma_f32_16x16x32_bf16 v[98:101], v[168:171], v[184:187], v[98:101]
	v_mfma_f32_16x16x32_bf16 v[90:93], v[160:163], v[192:195], v[90:93]
	v_mfma_f32_16x16x32_bf16 v[82:85], v[168:171], v[192:195], v[82:85]
	v_mfma_f32_16x16x32_bf16 v[74:77], v[160:163], v[214:217], v[74:77]
	v_mfma_f32_16x16x32_bf16 v[66:69], v[168:171], v[214:217], v[66:69]
	v_mfma_f32_16x16x32_bf16 v[122:125], v[164:167], v[180:183], v[122:125]
	v_mfma_f32_16x16x32_bf16 v[114:117], v[172:175], v[180:183], v[114:117]
	v_mfma_f32_16x16x32_bf16 v[106:109], v[164:167], v[188:191], v[106:109]
	v_mfma_f32_16x16x32_bf16 v[98:101], v[172:175], v[188:191], v[98:101]
	v_mfma_f32_16x16x32_bf16 v[90:93], v[164:167], v[202:205], v[90:93]
	v_mfma_f32_16x16x32_bf16 v[82:85], v[172:175], v[202:205], v[82:85]
	v_mfma_f32_16x16x32_bf16 v[74:77], v[164:167], v[224:227], v[74:77]
	v_mfma_f32_16x16x32_bf16 v[66:69], v[172:175], v[224:227], v[66:69]
	s_setprio 0
	s_barrier
	s_add_i32 s54, s54, s37
	v_lshl_add_u64 v[196:197], s[24:25], 0, v[0:1]
	s_mov_b32 m0, s54
	ds_read_b128 v[176:179], v143 offset:16384
	ds_read_b128 v[180:183], v143 offset:17408
	ds_read_b128 v[184:187], v143 offset:18432
	ds_read_b128 v[188:191], v143 offset:19456
	ds_read_b128 v[192:195], v143 offset:20480
	ds_read_b128 v[202:205], v143 offset:21504
	ds_read_b128 v[214:217], v143 offset:22528
	ds_read_b128 v[224:227], v143 offset:23552
	global_load_lds_dwordx4 v[196:197], off
	s_add_i32 m0, s54, 0x2000
	s_add_u32 s54, s24, 0x40000
	v_lshl_add_u64 v[198:199], s[24:25], 0, v[130:131]
	s_addc_u32 s55, s25, 0
	s_add_i32 s56, s56, s37
	global_load_lds_dwordx4 v[198:199], off
	v_lshl_add_u64 v[200:201], s[54:55], 0, v[0:1]
	s_mov_b32 m0, s56
	v_lshl_add_u64 v[206:207], s[26:27], 0, v[132:133]
	global_load_lds_dwordx4 v[200:201], off
	v_lshl_add_u64 v[200:201], s[54:55], 0, v[130:131]
	s_add_i32 m0, s56, 0x2000
	s_nop 0
	global_load_lds_dwordx4 v[200:201], off
	v_lshl_add_u64 v[200:201], s[26:27], 0, v[134:135]
	s_mov_b32 m0, s38
	s_nop 0
	global_load_lds_dwordx4 v[200:201], off
	s_mov_b32 m0, s39
	s_nop 0
	global_load_lds_dwordx4 v[206:207], off
	s_cmp_lg_u32 s53, 12
	s_cbranch_scc1 .Lp3w_nlA
	s_lshl_b32 s56, s47, 8
	s_add_i32 s56, s56, s42
	v_and_b32_e32 v228, 15, v212
	v_lshrrev_b32_e32 v229, 4, v212
	v_or_b32_e32 v228, s56, v228
	v_lshlrev_b32_e32 v228, 6, v228
	v_lshl_add_u32 v230, v229, 4, v228
	v_mov_b32_e32 v231, 0
	v_lshl_add_u64 v[250:251], s[6:7], 0, v[230:231]
	v_mov_b32_e32 v230, 0x2000
	v_lshl_add_u64 v[248:249], v[250:251], 0, v[230:231]
	global_load_dwordx4 v[228:231], v[250:251], off
	global_load_dwordx4 v[232:235], v[250:251], off offset:1024
	global_load_dwordx4 v[236:239], v[250:251], off offset:2048
	global_load_dwordx4 v[240:243], v[250:251], off offset:3072
	global_load_dwordx4 v[244:247], v[248:249], off
	s_nop 0
	global_load_dwordx4 v[248:251], v[248:249], off offset:1024
	s_waitcnt vmcnt(14)
	s_branch .Lp3w_jA
.Lp3w_nlA:
	s_cmp_eq_u32 s53, -2
	s_cbranch_scc1 .Lp3w_fA
	s_waitcnt vmcnt(8)
	s_branch .Lp3w_jA

.LBB0_1238:
	s_add_u32 s28, s26, 0xfffc0080
	s_addc_u32 s29, s27, -1
	s_add_i32 s52, 0, 0x10000
	s_cmp_eq_u32 s51, 12
	s_cselect_b32 s31, s15, s29
	s_cselect_b32 s30, s23, s28
	v_add_u32_e32 v140, s52, v141
	s_cselect_b32 s29, s13, s50
	s_cselect_b32 s28, s48, s49
	s_add_i32 s54, 0, 0x14000
	ds_read_b128 v[144:147], v140
	ds_read_b128 v[148:151], v140 offset:1024
	ds_read_b128 v[152:155], v140 offset:2048
	ds_read_b128 v[156:159], v140 offset:3072
	v_add_u32_e32 v140, s54, v141
	ds_read_b128 v[160:163], v140
	ds_read_b128 v[164:167], v140 offset:1024
	ds_read_b128 v[168:171], v140 offset:2048
	ds_read_b128 v[172:175], v140 offset:3072
	v_lshl_add_u64 v[210:211], s[26:27], 0, v[136:137]
	s_add_i32 m0, s25, 0xc000
	ds_read_b128 v[176:179], v143
	ds_read_b128 v[180:183], v143 offset:1024
	ds_read_b128 v[184:187], v143 offset:2048
	ds_read_b128 v[188:191], v143 offset:3072
	ds_read_b128 v[192:195], v143 offset:4096
	ds_read_b128 v[196:199], v143 offset:5120
	ds_read_b128 v[200:203], v143 offset:6144
	ds_read_b128 v[204:207], v143 offset:7168
	global_load_lds_dwordx4 v[210:211], off
	v_lshl_add_u64 v[210:211], s[26:27], 0, v[138:139]
	s_add_i32 m0, s25, 0xe000
	s_nop 0
	global_load_lds_dwordx4 v[210:211], off
	s_cmp_eq_u32 s51, -2
	s_cbranch_scc1 .Lp3r_f0
	s_waitcnt vmcnt(8)
	s_branch .Lp3r_j0
.Lp3r_f0:
	s_waitcnt vmcnt(18)
.Lp3r_j0:
	s_waitcnt lgkmcnt(0)
	s_barrier
	s_setprio 1
	s_waitcnt lgkmcnt(0)
	v_mfma_f32_16x16x32_bf16 v[126:129], v[144:147], v[176:179], v[126:129]
	v_mfma_f32_16x16x32_bf16 v[118:121], v[152:155], v[176:179], v[118:121]
	v_mfma_f32_16x16x32_bf16 v[110:113], v[144:147], v[184:187], v[110:113]
	v_mfma_f32_16x16x32_bf16 v[102:105], v[152:155], v[184:187], v[102:105]
	v_mfma_f32_16x16x32_bf16 v[94:97], v[144:147], v[192:195], v[94:97]
	v_mfma_f32_16x16x32_bf16 v[86:89], v[152:155], v[192:195], v[86:89]
	v_mfma_f32_16x16x32_bf16 v[78:81], v[144:147], v[200:203], v[78:81]
	v_mfma_f32_16x16x32_bf16 v[70:73], v[152:155], v[200:203], v[70:73]
	v_mfma_f32_16x16x32_bf16 v[126:129], v[148:151], v[180:183], v[126:129]
	v_mfma_f32_16x16x32_bf16 v[118:121], v[156:159], v[180:183], v[118:121]
	v_mfma_f32_16x16x32_bf16 v[110:113], v[148:151], v[188:191], v[110:113]
	v_mfma_f32_16x16x32_bf16 v[102:105], v[156:159], v[188:191], v[102:105]
	v_mfma_f32_16x16x32_bf16 v[94:97], v[148:151], v[196:199], v[94:97]
	v_mfma_f32_16x16x32_bf16 v[86:89], v[156:159], v[196:199], v[86:89]
	v_mfma_f32_16x16x32_bf16 v[78:81], v[148:151], v[204:207], v[78:81]
	v_mfma_f32_16x16x32_bf16 v[70:73], v[156:159], v[204:207], v[70:73]
	s_setprio 0
	s_setprio 1
	v_mfma_f32_16x16x32_bf16 v[122:125], v[160:163], v[176:179], v[122:125]
	v_mfma_f32_16x16x32_bf16 v[114:117], v[168:171], v[176:179], v[114:117]
	v_mfma_f32_16x16x32_bf16 v[106:109], v[160:163], v[184:187], v[106:109]
	v_mfma_f32_16x16x32_bf16 v[98:101], v[168:171], v[184:187], v[98:101]
	v_mfma_f32_16x16x32_bf16 v[90:93], v[160:163], v[192:195], v[90:93]
	v_mfma_f32_16x16x32_bf16 v[82:85], v[168:171], v[192:195], v[82:85]
	v_mfma_f32_16x16x32_bf16 v[74:77], v[160:163], v[200:203], v[74:77]
	v_mfma_f32_16x16x32_bf16 v[66:69], v[168:171], v[200:203], v[66:69]
	v_mfma_f32_16x16x32_bf16 v[122:125], v[164:167], v[180:183], v[122:125]
	v_mfma_f32_16x16x32_bf16 v[114:117], v[172:175], v[180:183], v[114:117]
	v_mfma_f32_16x16x32_bf16 v[106:109], v[164:167], v[188:191], v[106:109]
	v_mfma_f32_16x16x32_bf16 v[98:101], v[172:175], v[188:191], v[98:101]
	v_mfma_f32_16x16x32_bf16 v[90:93], v[164:167], v[196:199], v[90:93]
	v_mfma_f32_16x16x32_bf16 v[82:85], v[172:175], v[196:199], v[82:85]
	v_mfma_f32_16x16x32_bf16 v[74:77], v[164:167], v[204:207], v[74:77]
	v_mfma_f32_16x16x32_bf16 v[66:69], v[172:175], v[204:207], v[66:69]
	s_setprio 0
	s_barrier
	s_add_i32 s52, s52, s39
	v_lshl_add_u64 v[210:211], s[28:29], 0, v[0:1]
	s_mov_b32 m0, s52
	ds_read_b128 v[176:179], v143 offset:16384
	ds_read_b128 v[180:183], v143 offset:17408
	ds_read_b128 v[184:187], v143 offset:18432
	ds_read_b128 v[188:191], v143 offset:19456
	ds_read_b128 v[192:195], v143 offset:20480
	ds_read_b128 v[196:199], v143 offset:21504
	ds_read_b128 v[200:203], v143 offset:22528
	ds_read_b128 v[204:207], v143 offset:23552
	global_load_lds_dwordx4 v[210:211], off
	s_add_i32 m0, s52, 0x2000
	s_add_u32 s52, s28, 0x40000
	v_lshl_add_u64 v[214:215], s[28:29], 0, v[130:131]
	s_addc_u32 s53, s29, 0
	s_add_i32 s54, s54, s39
	global_load_lds_dwordx4 v[214:215], off
	v_lshl_add_u64 v[216:217], s[52:53], 0, v[0:1]
	s_mov_b32 m0, s54
	v_lshl_add_u64 v[224:225], s[30:31], 0, v[132:133]
	global_load_lds_dwordx4 v[216:217], off
	v_lshl_add_u64 v[216:217], s[52:53], 0, v[130:131]
	s_add_i32 m0, s54, 0x2000
	s_nop 0
	global_load_lds_dwordx4 v[216:217], off
	v_lshl_add_u64 v[216:217], s[30:31], 0, v[134:135]
	s_mov_b32 m0, s25
	s_nop 0
	global_load_lds_dwordx4 v[216:217], off
	s_mov_b32 m0, s40
	s_nop 0
	global_load_lds_dwordx4 v[224:225], off
	s_cmp_lg_u32 s51, 12
	s_cbranch_scc1 .Lp3r_nlA
	s_lshl_b32 s54, s22, 8
	s_add_i32 s54, s54, s43
	v_and_b32_e32 v228, 15, v212
	v_lshrrev_b32_e32 v229, 4, v212
	v_or_b32_e32 v228, s54, v228
	v_lshlrev_b32_e32 v228, 6, v228
	v_lshl_add_u32 v230, v229, 4, v228
	v_mov_b32_e32 v231, 0
	v_lshl_add_u64 v[250:251], s[4:5], 0, v[230:231]
	v_mov_b32_e32 v230, 0x2000
	v_lshl_add_u64 v[248:249], v[250:251], 0, v[230:231]
	global_load_dwordx4 v[228:231], v[250:251], off
	global_load_dwordx4 v[232:235], v[250:251], off offset:1024
	global_load_dwordx4 v[236:239], v[250:251], off offset:2048
	global_load_dwordx4 v[240:243], v[250:251], off offset:3072
	global_load_dwordx4 v[244:247], v[248:249], off
	s_nop 0
	global_load_dwordx4 v[248:251], v[248:249], off offset:1024
	s_waitcnt vmcnt(14)
	s_branch .Lp3r_jA
.Lp3r_nlA:
	s_cmp_eq_u32 s51, -2
	s_cbranch_scc1 .Lp3r_fA
	s_waitcnt vmcnt(8)
	s_branch .Lp3r_jA
